# snake MFMA order everywhere + P8 K-loop merged to 64-MFMA slots with role-split saddr LDS-DMA staging and 64-long snake
# speedup vs baseline: 1.0689x; 1.0023x over previous
; #define PG8_STAGE(bufoff, gbase, voff) do { _Pragma("unroll") for (int _i = 0; _i < 2; ++_i) \
;         __builtin_amdgcn_global_load_lds((const unsigned*)((const char*)(gbase) + (voff)[_i]), (PG8_LAS unsigned*)(lds + (bufoff) + ldsw + _i * 8192), 16, 0, 0); } while (0)
; #define PG8_LDA(dst, b, h) do { _Pragma("unroll") for (int m = 0; m < 4; ++m) _Pragma("unroll") for (int k = 0; k < 2; ++k) dst[m][k] = *(const PG8_LAS bf16x8*)(lds + PG8_SA(b, h) + aoff + m * 2048 + k * 1024); } while (0)
; #define PG8_LDB(dst, b, h) do { _Pragma("unroll") for (int n = 0; n < 2; ++n) _Pragma("unroll") for (int k = 0; k < 2; ++k) dst[n][k] = *(const PG8_LAS bf16x8*)(lds + PG8_SB(b, h) + boff + n * 2048 + k * 1024); } while (0)
; #define PG8_MMA(ai, bj, At, Bt) do { __builtin_amdgcn_s_setprio(1); _Pragma("unroll") for (int m = 0; m < 4; ++m) _Pragma("unroll") for (int n = 0; n < 2; ++n) _Pragma("unroll") for (int k = 0; k < 2; ++k) \
;         acc[ai][bj][m][n] = __builtin_amdgcn_mfma_f32_16x16x32_bf16(Bt[n][k], At[m][k], acc[ai][bj][m][n], 0, 0, 0); __builtin_amdgcn_s_setprio(0); } while (0)
; #define PG8_WAIT_V(n) asm volatile("s_waitcnt vmcnt(" #n ")" ::: "memory")
; #define PG8_WAIT_L(n) asm volatile("s_waitcnt lgkmcnt(" #n ")" ::: "memory")
; #define PG8_BAR __builtin_amdgcn_s_barrier()
; #define PG8_SCHED __builtin_amdgcn_sched_barrier(0)
; template <class Epi, class Sched, bool ALIGN_EPI>
; __device__ __forceinline__ void gemm_phase(PG8_LAS unsigned char* lds, const Gemm g, const Sched& S, const Epi& E) {
;     ...
;             PG8_LDB(B0, 0, 0); PG8_LDB(B1, 0, 1); PG8_SCHED; PG8_LDA(At, 0, 0); PG8_STAGE(PG8_SA(1, 1), a1 + hstepA, voffA);
;             PG8_WAIT_V(8); PG8_WAIT_L(0); PG8_BAR; PG8_MMA(0, 0, At, B0); PG8_MMA(0, 1, At, B1); PG8_BAR; PG8_SCHED;
;             PG8_LDA(At, 0, 1); PG8_STAGE(PG8_SB(0, 0), b2, voffB); PG8_STAGE(PG8_SB(0, 1), b2 + hstepB, voffB); PG8_STAGE(PG8_SA(0, 0), a2, voffA);
;             PG8_WAIT_V(8); PG8_WAIT_L(0); PG8_BAR; PG8_MMA(1, 0, At, B0); PG8_MMA(1, 1, At, B1); PG8_BAR; PG8_SCHED;
; __global__ void __launch_bounds__(NWAVES * 64, 2) hymba_fwd(Args a) {
;     ...
;         pg8::Gemm g{R1, Wgu_t, DM, DM, DM}; pg8::StaticOrder S; S.init(M, 2 * D_FF, G, bx);
;         pg8::EpiSwiGLU E{HID, D_FF, (const float*)(ws + WS_RH)};
;         pg8::gemm_phase<pg8::EpiSwiGLU, pg8::StaticOrder, true>(lds, g, S, E);
.Lp8k_A_loop:
	s_add_i32 m0, s2, 0x18000
	s_nop 0
	global_load_lds_dwordx4 v134, s[28:29]
	s_add_i32 m0, s2, 0x1a000
	s_nop 0
	global_load_lds_dwordx4 v130, s[28:29]
	s_add_u32 s30, s28, 0x20000
	s_addc_u32 s31, s29, 0
	s_add_i32 m0, s2, 0x19000
	s_nop 0
	global_load_lds_dwordx4 v134, s[30:31]
	s_add_i32 m0, s2, 0x1b000
	s_nop 0
	global_load_lds_dwordx4 v130, s[30:31]
	s_add_u32 s30, s28, 0x80000
	s_addc_u32 s31, s29, 0
	s_add_i32 m0, s2, 0x1c000
	s_nop 0
	global_load_lds_dwordx4 v134, s[30:31]
	s_add_i32 m0, s2, 0x1e000
	s_nop 0
	global_load_lds_dwordx4 v130, s[30:31]
	s_add_u32 s30, s28, 0xa0000
	s_addc_u32 s31, s29, 0
	s_add_i32 m0, s2, 0x1d000
	s_nop 0
	global_load_lds_dwordx4 v134, s[30:31]
	s_add_i32 m0, s2, 0x1f000
	s_nop 0
	global_load_lds_dwordx4 v130, s[30:31]
	s_add_u32 s28, s28, 0x80
	s_addc_u32 s29, s29, 0
	ds_read_b128 v[190:193], v155 offset:0
	ds_read_b128 v[194:197], v155 offset:1024
	ds_read_b128 v[198:201], v155 offset:2048
	ds_read_b128 v[202:205], v155 offset:3072
	ds_read_b128 v[206:209], v155 offset:4096
	ds_read_b128 v[210:213], v155 offset:5120
	ds_read_b128 v[214:217], v155 offset:6144
	ds_read_b128 v[218:221], v155 offset:7168
	ds_read_b128 v[156:159], v153 offset:0
	ds_read_b128 v[160:163], v153 offset:1024
	ds_read_b128 v[164:167], v153 offset:2048
	ds_read_b128 v[168:171], v153 offset:3072
	ds_read_b128 v[174:177], v153 offset:16384
	ds_read_b128 v[178:181], v153 offset:17408
	ds_read_b128 v[182:185], v153 offset:18432
	ds_read_b128 v[186:189], v153 offset:19456
	ds_read_b128 v[222:225], v155 offset:16384
	ds_read_b128 v[226:229], v155 offset:17408
	ds_read_b128 v[230:233], v155 offset:18432
	ds_read_b128 v[234:237], v155 offset:19456
	ds_read_b128 v[238:241], v155 offset:20480
	ds_read_b128 v[242:245], v155 offset:21504
	ds_read_b128 v[246:249], v155 offset:22528
	ds_read_b128 v[250:253], v155 offset:23552
	s_waitcnt vmcnt(8) lgkmcnt(0)
	s_barrier
	s_setprio 1
	v_mfma_f32_16x16x32_bf16 v[126:129], v[156:159], v[190:193], v[126:129]
	v_mfma_f32_16x16x32_bf16 v[126:129], v[160:163], v[194:197], v[126:129]
	v_mfma_f32_16x16x32_bf16 v[122:125], v[168:171], v[194:197], v[122:125]
	v_mfma_f32_16x16x32_bf16 v[122:125], v[164:167], v[190:193], v[122:125]
	v_mfma_f32_16x16x32_bf16 v[118:121], v[174:177], v[190:193], v[118:121]
	v_mfma_f32_16x16x32_bf16 v[118:121], v[178:181], v[194:197], v[118:121]
	v_mfma_f32_16x16x32_bf16 v[114:117], v[186:189], v[194:197], v[114:117]
	v_mfma_f32_16x16x32_bf16 v[114:117], v[182:185], v[190:193], v[114:117]
	v_mfma_f32_16x16x32_bf16 v[98:101], v[182:185], v[198:201], v[98:101]
	v_mfma_f32_16x16x32_bf16 v[98:101], v[186:189], v[202:205], v[98:101]
	v_mfma_f32_16x16x32_bf16 v[102:105], v[178:181], v[202:205], v[102:105]
	v_mfma_f32_16x16x32_bf16 v[102:105], v[174:177], v[198:201], v[102:105]
	v_mfma_f32_16x16x32_bf16 v[106:109], v[164:167], v[198:201], v[106:109]
	v_mfma_f32_16x16x32_bf16 v[106:109], v[168:171], v[202:205], v[106:109]
	v_mfma_f32_16x16x32_bf16 v[110:113], v[160:163], v[202:205], v[110:113]
	v_mfma_f32_16x16x32_bf16 v[110:113], v[156:159], v[198:201], v[110:113]
	v_mfma_f32_16x16x32_bf16 v[94:97], v[156:159], v[206:209], v[94:97]
	v_mfma_f32_16x16x32_bf16 v[94:97], v[160:163], v[210:213], v[94:97]
	v_mfma_f32_16x16x32_bf16 v[90:93], v[168:171], v[210:213], v[90:93]
	v_mfma_f32_16x16x32_bf16 v[90:93], v[164:167], v[206:209], v[90:93]
	v_mfma_f32_16x16x32_bf16 v[86:89], v[174:177], v[206:209], v[86:89]
	v_mfma_f32_16x16x32_bf16 v[86:89], v[178:181], v[210:213], v[86:89]
	v_mfma_f32_16x16x32_bf16 v[82:85], v[186:189], v[210:213], v[82:85]
	v_mfma_f32_16x16x32_bf16 v[82:85], v[182:185], v[206:209], v[82:85]
	v_mfma_f32_16x16x32_bf16 v[66:69], v[182:185], v[214:217], v[66:69]
	v_mfma_f32_16x16x32_bf16 v[66:69], v[186:189], v[218:221], v[66:69]
	v_mfma_f32_16x16x32_bf16 v[70:73], v[178:181], v[218:221], v[70:73]
	v_mfma_f32_16x16x32_bf16 v[70:73], v[174:177], v[214:217], v[70:73]
	v_mfma_f32_16x16x32_bf16 v[74:77], v[164:167], v[214:217], v[74:77]
	v_mfma_f32_16x16x32_bf16 v[74:77], v[168:171], v[218:221], v[74:77]
	v_mfma_f32_16x16x32_bf16 v[78:81], v[160:163], v[218:221], v[78:81]
	v_mfma_f32_16x16x32_bf16 v[78:81], v[156:159], v[214:217], v[78:81]
	v_mfma_f32_16x16x32_bf16 v[62:65], v[156:159], v[222:225], v[62:65]
	v_mfma_f32_16x16x32_bf16 v[62:65], v[160:163], v[226:229], v[62:65]
	v_mfma_f32_16x16x32_bf16 v[58:61], v[168:171], v[226:229], v[58:61]
	v_mfma_f32_16x16x32_bf16 v[58:61], v[164:167], v[222:225], v[58:61]
	v_mfma_f32_16x16x32_bf16 v[54:57], v[174:177], v[222:225], v[54:57]
	v_mfma_f32_16x16x32_bf16 v[54:57], v[178:181], v[226:229], v[54:57]
	v_mfma_f32_16x16x32_bf16 v[50:53], v[186:189], v[226:229], v[50:53]
	v_mfma_f32_16x16x32_bf16 v[50:53], v[182:185], v[222:225], v[50:53]
	v_mfma_f32_16x16x32_bf16 v[34:37], v[182:185], v[230:233], v[34:37]
	v_mfma_f32_16x16x32_bf16 v[34:37], v[186:189], v[234:237], v[34:37]
	v_mfma_f32_16x16x32_bf16 v[38:41], v[178:181], v[234:237], v[38:41]
	v_mfma_f32_16x16x32_bf16 v[38:41], v[174:177], v[230:233], v[38:41]
	v_mfma_f32_16x16x32_bf16 v[42:45], v[164:167], v[230:233], v[42:45]
	v_mfma_f32_16x16x32_bf16 v[42:45], v[168:171], v[234:237], v[42:45]
	v_mfma_f32_16x16x32_bf16 v[46:49], v[160:163], v[234:237], v[46:49]
	v_mfma_f32_16x16x32_bf16 v[46:49], v[156:159], v[230:233], v[46:49]
	v_mfma_f32_16x16x32_bf16 v[30:33], v[156:159], v[238:241], v[30:33]
	v_mfma_f32_16x16x32_bf16 v[30:33], v[160:163], v[242:245], v[30:33]
	v_mfma_f32_16x16x32_bf16 v[26:29], v[168:171], v[242:245], v[26:29]
	v_mfma_f32_16x16x32_bf16 v[26:29], v[164:167], v[238:241], v[26:29]
	v_mfma_f32_16x16x32_bf16 v[22:25], v[174:177], v[238:241], v[22:25]
	v_mfma_f32_16x16x32_bf16 v[22:25], v[178:181], v[242:245], v[22:25]
	v_mfma_f32_16x16x32_bf16 v[18:21], v[186:189], v[242:245], v[18:21]
	v_mfma_f32_16x16x32_bf16 v[18:21], v[182:185], v[238:241], v[18:21]
	v_mfma_f32_16x16x32_bf16 v[2:5], v[182:185], v[246:249], v[2:5]
	v_mfma_f32_16x16x32_bf16 v[2:5], v[186:189], v[250:253], v[2:5]
	v_mfma_f32_16x16x32_bf16 v[6:9], v[178:181], v[250:253], v[6:9]
	v_mfma_f32_16x16x32_bf16 v[6:9], v[174:177], v[246:249], v[6:9]
	v_mfma_f32_16x16x32_bf16 v[10:13], v[164:167], v[246:249], v[10:13]
	v_mfma_f32_16x16x32_bf16 v[10:13], v[168:171], v[250:253], v[10:13]
	v_mfma_f32_16x16x32_bf16 v[14:17], v[160:163], v[250:253], v[14:17]
	v_mfma_f32_16x16x32_bf16 v[14:17], v[156:159], v[246:249], v[14:17]
	s_setprio 0
	s_waitcnt vmcnt(0)
	s_barrier
; #define PG8_STAGE(bufoff, gbase, voff) do { _Pragma("unroll") for (int _i = 0; _i < 2; ++_i) \
;         __builtin_amdgcn_global_load_lds((const unsigned*)((const char*)(gbase) + (voff)[_i]), (PG8_LAS unsigned*)(lds + (bufoff) + ldsw + _i * 8192), 16, 0, 0); } while (0)
; #define PG8_LDA(dst, b, h) do { _Pragma("unroll") for (int m = 0; m < 4; ++m) _Pragma("unroll") for (int k = 0; k < 2; ++k) dst[m][k] = *(const PG8_LAS bf16x8*)(lds + PG8_SA(b, h) + aoff + m * 2048 + k * 1024); } while (0)
; #define PG8_LDB(dst, b, h) do { _Pragma("unroll") for (int n = 0; n < 2; ++n) _Pragma("unroll") for (int k = 0; k < 2; ++k) dst[n][k] = *(const PG8_LAS bf16x8*)(lds + PG8_SB(b, h) + boff + n * 2048 + k * 1024); } while (0)
; #define PG8_MMA(ai, bj, At, Bt) do { __builtin_amdgcn_s_setprio(1); _Pragma("unroll") for (int m = 0; m < 4; ++m) _Pragma("unroll") for (int n = 0; n < 2; ++n) _Pragma("unroll") for (int k = 0; k < 2; ++k) \
;         acc[ai][bj][m][n] = __builtin_amdgcn_mfma_f32_16x16x32_bf16(Bt[n][k], At[m][k], acc[ai][bj][m][n], 0, 0, 0); __builtin_amdgcn_s_setprio(0); } while (0)
; #define PG8_WAIT_V(n) asm volatile("s_waitcnt vmcnt(" #n ")" ::: "memory")
; #define PG8_WAIT_L(n) asm volatile("s_waitcnt lgkmcnt(" #n ")" ::: "memory")
; #define PG8_BAR __builtin_amdgcn_s_barrier()
; #define PG8_SCHED __builtin_amdgcn_sched_barrier(0)
; template <class Epi, class Sched, bool ALIGN_EPI>
; __device__ __forceinline__ void gemm_phase(PG8_LAS unsigned char* lds, const Gemm g, const Sched& S, const Epi& E) {
;     ...
;             PG8_LDB(B0, 1, 0); PG8_LDB(B1, 1, 1); PG8_SCHED; PG8_LDA(At, 1, 0); PG8_STAGE(PG8_SA(0, 1), a2 + hstepA, voffA);
;             PG8_WAIT_V(8); PG8_WAIT_L(0); PG8_BAR; PG8_MMA(0, 0, At, B0); PG8_MMA(0, 1, At, B1); PG8_BAR; PG8_SCHED;
;             PG8_LDA(At, 1, 1); PG8_STAGE(PG8_SB(1, 0), b3, voffB); PG8_STAGE(PG8_SB(1, 1), b3 + hstepB, voffB); PG8_STAGE(PG8_SA(1, 0), a3, voffA);
;             PG8_WAIT_V(8); PG8_WAIT_L(0); PG8_BAR; PG8_MMA(1, 0, At, B0); PG8_MMA(1, 1, At, B1); PG8_BAR; PG8_SCHED;
;         }
	s_cmp_eq_u32 s49, 15
	s_cselect_b32 s28, s50, s28
	s_cselect_b32 s29, s51, s29
	s_add_i32 m0, s2, 0x10000
	s_nop 0
	global_load_lds_dwordx4 v134, s[28:29]
	s_add_i32 m0, s2, 0x12000
	s_nop 0
	global_load_lds_dwordx4 v130, s[28:29]
	s_add_u32 s30, s28, 0x20000
	s_addc_u32 s31, s29, 0
	s_add_i32 m0, s2, 0x11000
	s_nop 0
	global_load_lds_dwordx4 v134, s[30:31]
	s_add_i32 m0, s2, 0x13000
	s_nop 0
	global_load_lds_dwordx4 v130, s[30:31]
	s_add_u32 s30, s28, 0x80000
	s_addc_u32 s31, s29, 0
	s_add_i32 m0, s2, 0x14000
	s_nop 0
	global_load_lds_dwordx4 v134, s[30:31]
	s_add_i32 m0, s2, 0x16000
	s_nop 0
	global_load_lds_dwordx4 v130, s[30:31]
	s_add_u32 s30, s28, 0xa0000
	s_addc_u32 s31, s29, 0
	s_add_i32 m0, s2, 0x15000
	s_nop 0
	global_load_lds_dwordx4 v134, s[30:31]
	s_add_i32 m0, s2, 0x17000
	s_nop 0
	global_load_lds_dwordx4 v130, s[30:31]
	s_add_u32 s28, s28, 0x80
	s_addc_u32 s29, s29, 0
	ds_read_b128 v[190:193], v155 offset:32768
	ds_read_b128 v[194:197], v155 offset:33792
	ds_read_b128 v[198:201], v155 offset:34816
	ds_read_b128 v[202:205], v155 offset:35840
	ds_read_b128 v[206:209], v155 offset:36864
	ds_read_b128 v[210:213], v155 offset:37888
	ds_read_b128 v[214:217], v155 offset:38912
	ds_read_b128 v[218:221], v155 offset:39936
	ds_read_b128 v[156:159], v153 offset:32768
	ds_read_b128 v[160:163], v153 offset:33792
	ds_read_b128 v[164:167], v153 offset:34816
	ds_read_b128 v[168:171], v153 offset:35840
	ds_read_b128 v[174:177], v153 offset:49152
	ds_read_b128 v[178:181], v153 offset:50176
	ds_read_b128 v[182:185], v153 offset:51200
	ds_read_b128 v[186:189], v153 offset:52224
	ds_read_b128 v[222:225], v155 offset:49152
	ds_read_b128 v[226:229], v155 offset:50176
	ds_read_b128 v[230:233], v155 offset:51200
	ds_read_b128 v[234:237], v155 offset:52224
	ds_read_b128 v[238:241], v155 offset:53248
	ds_read_b128 v[242:245], v155 offset:54272
	ds_read_b128 v[246:249], v155 offset:55296
	ds_read_b128 v[250:253], v155 offset:56320
	s_waitcnt vmcnt(8) lgkmcnt(0)
	s_barrier
	s_setprio 1
	v_mfma_f32_16x16x32_bf16 v[126:129], v[156:159], v[190:193], v[126:129]
	v_mfma_f32_16x16x32_bf16 v[126:129], v[160:163], v[194:197], v[126:129]
	v_mfma_f32_16x16x32_bf16 v[122:125], v[168:171], v[194:197], v[122:125]
	v_mfma_f32_16x16x32_bf16 v[122:125], v[164:167], v[190:193], v[122:125]
	v_mfma_f32_16x16x32_bf16 v[118:121], v[174:177], v[190:193], v[118:121]
	v_mfma_f32_16x16x32_bf16 v[118:121], v[178:181], v[194:197], v[118:121]
	v_mfma_f32_16x16x32_bf16 v[114:117], v[186:189], v[194:197], v[114:117]
	v_mfma_f32_16x16x32_bf16 v[114:117], v[182:185], v[190:193], v[114:117]
	v_mfma_f32_16x16x32_bf16 v[98:101], v[182:185], v[198:201], v[98:101]
	v_mfma_f32_16x16x32_bf16 v[98:101], v[186:189], v[202:205], v[98:101]
	v_mfma_f32_16x16x32_bf16 v[102:105], v[178:181], v[202:205], v[102:105]
	v_mfma_f32_16x16x32_bf16 v[102:105], v[174:177], v[198:201], v[102:105]
	v_mfma_f32_16x16x32_bf16 v[106:109], v[164:167], v[198:201], v[106:109]
	v_mfma_f32_16x16x32_bf16 v[106:109], v[168:171], v[202:205], v[106:109]
	v_mfma_f32_16x16x32_bf16 v[110:113], v[160:163], v[202:205], v[110:113]
	v_mfma_f32_16x16x32_bf16 v[110:113], v[156:159], v[198:201], v[110:113]
	v_mfma_f32_16x16x32_bf16 v[94:97], v[156:159], v[206:209], v[94:97]
	v_mfma_f32_16x16x32_bf16 v[94:97], v[160:163], v[210:213], v[94:97]
	v_mfma_f32_16x16x32_bf16 v[90:93], v[168:171], v[210:213], v[90:93]
	v_mfma_f32_16x16x32_bf16 v[90:93], v[164:167], v[206:209], v[90:93]
	v_mfma_f32_16x16x32_bf16 v[86:89], v[174:177], v[206:209], v[86:89]
	v_mfma_f32_16x16x32_bf16 v[86:89], v[178:181], v[210:213], v[86:89]
	v_mfma_f32_16x16x32_bf16 v[82:85], v[186:189], v[210:213], v[82:85]
	v_mfma_f32_16x16x32_bf16 v[82:85], v[182:185], v[206:209], v[82:85]
	v_mfma_f32_16x16x32_bf16 v[66:69], v[182:185], v[214:217], v[66:69]
	v_mfma_f32_16x16x32_bf16 v[66:69], v[186:189], v[218:221], v[66:69]
	v_mfma_f32_16x16x32_bf16 v[70:73], v[178:181], v[218:221], v[70:73]
	v_mfma_f32_16x16x32_bf16 v[70:73], v[174:177], v[214:217], v[70:73]
	v_mfma_f32_16x16x32_bf16 v[74:77], v[164:167], v[214:217], v[74:77]
	v_mfma_f32_16x16x32_bf16 v[74:77], v[168:171], v[218:221], v[74:77]
	v_mfma_f32_16x16x32_bf16 v[78:81], v[160:163], v[218:221], v[78:81]
	v_mfma_f32_16x16x32_bf16 v[78:81], v[156:159], v[214:217], v[78:81]
	v_mfma_f32_16x16x32_bf16 v[62:65], v[156:159], v[222:225], v[62:65]
	v_mfma_f32_16x16x32_bf16 v[62:65], v[160:163], v[226:229], v[62:65]
	v_mfma_f32_16x16x32_bf16 v[58:61], v[168:171], v[226:229], v[58:61]
	v_mfma_f32_16x16x32_bf16 v[58:61], v[164:167], v[222:225], v[58:61]
	v_mfma_f32_16x16x32_bf16 v[54:57], v[174:177], v[222:225], v[54:57]
	v_mfma_f32_16x16x32_bf16 v[54:57], v[178:181], v[226:229], v[54:57]
	v_mfma_f32_16x16x32_bf16 v[50:53], v[186:189], v[226:229], v[50:53]
	v_mfma_f32_16x16x32_bf16 v[50:53], v[182:185], v[222:225], v[50:53]
	v_mfma_f32_16x16x32_bf16 v[34:37], v[182:185], v[230:233], v[34:37]
	v_mfma_f32_16x16x32_bf16 v[34:37], v[186:189], v[234:237], v[34:37]
	v_mfma_f32_16x16x32_bf16 v[38:41], v[178:181], v[234:237], v[38:41]
	v_mfma_f32_16x16x32_bf16 v[38:41], v[174:177], v[230:233], v[38:41]
	v_mfma_f32_16x16x32_bf16 v[42:45], v[164:167], v[230:233], v[42:45]
	v_mfma_f32_16x16x32_bf16 v[42:45], v[168:171], v[234:237], v[42:45]
	v_mfma_f32_16x16x32_bf16 v[46:49], v[160:163], v[234:237], v[46:49]
	v_mfma_f32_16x16x32_bf16 v[46:49], v[156:159], v[230:233], v[46:49]
	v_mfma_f32_16x16x32_bf16 v[30:33], v[156:159], v[238:241], v[30:33]
	v_mfma_f32_16x16x32_bf16 v[30:33], v[160:163], v[242:245], v[30:33]
	v_mfma_f32_16x16x32_bf16 v[26:29], v[168:171], v[242:245], v[26:29]
	v_mfma_f32_16x16x32_bf16 v[26:29], v[164:167], v[238:241], v[26:29]
	v_mfma_f32_16x16x32_bf16 v[22:25], v[174:177], v[238:241], v[22:25]
	v_mfma_f32_16x16x32_bf16 v[22:25], v[178:181], v[242:245], v[22:25]
	v_mfma_f32_16x16x32_bf16 v[18:21], v[186:189], v[242:245], v[18:21]
	v_mfma_f32_16x16x32_bf16 v[18:21], v[182:185], v[238:241], v[18:21]
	v_mfma_f32_16x16x32_bf16 v[2:5], v[182:185], v[246:249], v[2:5]
	v_mfma_f32_16x16x32_bf16 v[2:5], v[186:189], v[250:253], v[2:5]
	v_mfma_f32_16x16x32_bf16 v[6:9], v[178:181], v[250:253], v[6:9]
	v_mfma_f32_16x16x32_bf16 v[6:9], v[174:177], v[246:249], v[6:9]
	v_mfma_f32_16x16x32_bf16 v[10:13], v[164:167], v[246:249], v[10:13]
	v_mfma_f32_16x16x32_bf16 v[10:13], v[168:171], v[250:253], v[10:13]
	v_mfma_f32_16x16x32_bf16 v[14:17], v[160:163], v[250:253], v[14:17]
	v_mfma_f32_16x16x32_bf16 v[14:17], v[156:159], v[246:249], v[14:17]
	s_setprio 0
	s_waitcnt vmcnt(0)
	s_barrier
	s_add_i32 s49, s49, 1
	s_cmp_lt_u32 s49, 16
	s_cbranch_scc1 .Lp8k_A_loop
	s_branch .Lp8k_done

; #define PG8_STAGE(bufoff, gbase, voff) do { _Pragma("unroll") for (int _i = 0; _i < 2; ++_i) \
;         __builtin_amdgcn_global_load_lds((const unsigned*)((const char*)(gbase) + (voff)[_i]), (PG8_LAS unsigned*)(lds + (bufoff) + ldsw + _i * 8192), 16, 0, 0); } while (0)
; #define PG8_LDA(dst, b, h) do { _Pragma("unroll") for (int m = 0; m < 4; ++m) _Pragma("unroll") for (int k = 0; k < 2; ++k) dst[m][k] = *(const PG8_LAS bf16x8*)(lds + PG8_SA(b, h) + aoff + m * 2048 + k * 1024); } while (0)
; #define PG8_LDB(dst, b, h) do { _Pragma("unroll") for (int n = 0; n < 2; ++n) _Pragma("unroll") for (int k = 0; k < 2; ++k) dst[n][k] = *(const PG8_LAS bf16x8*)(lds + PG8_SB(b, h) + boff + n * 2048 + k * 1024); } while (0)
; #define PG8_MMA(ai, bj, At, Bt) do { __builtin_amdgcn_s_setprio(1); _Pragma("unroll") for (int m = 0; m < 4; ++m) _Pragma("unroll") for (int n = 0; n < 2; ++n) _Pragma("unroll") for (int k = 0; k < 2; ++k) \
;         acc[ai][bj][m][n] = __builtin_amdgcn_mfma_f32_16x16x32_bf16(Bt[n][k], At[m][k], acc[ai][bj][m][n], 0, 0, 0); __builtin_amdgcn_s_setprio(0); } while (0)
; #define PG8_WAIT_V(n) asm volatile("s_waitcnt vmcnt(" #n ")" ::: "memory")
; #define PG8_WAIT_L(n) asm volatile("s_waitcnt lgkmcnt(" #n ")" ::: "memory")
; #define PG8_BAR __builtin_amdgcn_s_barrier()
; #define PG8_SCHED __builtin_amdgcn_sched_barrier(0)
; template <class Epi, class Sched, bool ALIGN_EPI>
; __device__ __forceinline__ void gemm_phase(PG8_LAS unsigned char* lds, const Gemm g, const Sched& S, const Epi& E) {
;     ...
;             PG8_LDB(B0, 0, 0); PG8_LDB(B1, 0, 1); PG8_SCHED; PG8_LDA(At, 0, 0); PG8_STAGE(PG8_SA(1, 1), a1 + hstepA, voffA);
;             PG8_WAIT_V(8); PG8_WAIT_L(0); PG8_BAR; PG8_MMA(0, 0, At, B0); PG8_MMA(0, 1, At, B1); PG8_BAR; PG8_SCHED;
;             PG8_LDA(At, 0, 1); PG8_STAGE(PG8_SB(0, 0), b2, voffB); PG8_STAGE(PG8_SB(0, 1), b2 + hstepB, voffB); PG8_STAGE(PG8_SA(0, 0), a2, voffA);
;             PG8_WAIT_V(8); PG8_WAIT_L(0); PG8_BAR; PG8_MMA(1, 0, At, B0); PG8_MMA(1, 1, At, B1); PG8_BAR; PG8_SCHED;
.Lp8k_B_loop:
	s_add_i32 m0, s2, 0xa000
	s_nop 0
	global_load_lds_dwordx4 v132, s[28:29]
	s_add_u32 s30, s28, 0x20000
	s_addc_u32 s31, s29, 0
	s_add_i32 m0, s2, 0xb000
	s_nop 0
	global_load_lds_dwordx4 v132, s[30:31]
	s_add_u32 s30, s28, 0x80000
	s_addc_u32 s31, s29, 0
	s_add_i32 m0, s2, 0xe000
	s_nop 0
	global_load_lds_dwordx4 v132, s[30:31]
	s_add_u32 s30, s28, 0xa0000
	s_addc_u32 s31, s29, 0
	s_add_i32 m0, s2, 0xf000
	s_nop 0
	global_load_lds_dwordx4 v132, s[30:31]
	s_add_u32 s34, s28, 0x80
	s_addc_u32 s35, s29, 0
	s_cmp_eq_u32 s49, 15
	s_cselect_b32 s34, s50, s34
	s_cselect_b32 s35, s51, s35
	s_add_i32 m0, s2, 0x0
	s_nop 0
	global_load_lds_dwordx4 v136, s[34:35]
	s_add_u32 s30, s34, 0x20000
	s_addc_u32 s31, s35, 0
	s_add_i32 m0, s2, 0x1000
	s_nop 0
	global_load_lds_dwordx4 v136, s[30:31]
	s_add_u32 s30, s34, 0x80000
	s_addc_u32 s31, s35, 0
	s_add_i32 m0, s2, 0x4000
	s_nop 0
	global_load_lds_dwordx4 v136, s[30:31]
	s_add_u32 s30, s34, 0xa0000
	s_addc_u32 s31, s35, 0
	s_add_i32 m0, s2, 0x5000
	s_nop 0
	global_load_lds_dwordx4 v136, s[30:31]
	s_add_u32 s28, s28, 0x80
	s_addc_u32 s29, s29, 0
	ds_read_b128 v[190:193], v155 offset:0
	ds_read_b128 v[194:197], v155 offset:1024
	ds_read_b128 v[198:201], v155 offset:2048
	ds_read_b128 v[202:205], v155 offset:3072
	ds_read_b128 v[206:209], v155 offset:4096
	ds_read_b128 v[210:213], v155 offset:5120
	ds_read_b128 v[214:217], v155 offset:6144
	ds_read_b128 v[218:221], v155 offset:7168
	ds_read_b128 v[156:159], v153 offset:0
	ds_read_b128 v[160:163], v153 offset:1024
	ds_read_b128 v[164:167], v153 offset:2048
	ds_read_b128 v[168:171], v153 offset:3072
	ds_read_b128 v[174:177], v153 offset:16384
	ds_read_b128 v[178:181], v153 offset:17408
	ds_read_b128 v[182:185], v153 offset:18432
	ds_read_b128 v[186:189], v153 offset:19456
	ds_read_b128 v[222:225], v155 offset:16384
	ds_read_b128 v[226:229], v155 offset:17408
	ds_read_b128 v[230:233], v155 offset:18432
	ds_read_b128 v[234:237], v155 offset:19456
	ds_read_b128 v[238:241], v155 offset:20480
	ds_read_b128 v[242:245], v155 offset:21504
	ds_read_b128 v[246:249], v155 offset:22528
	ds_read_b128 v[250:253], v155 offset:23552
	s_waitcnt vmcnt(8) lgkmcnt(0)
	s_barrier
	s_setprio 1
	v_mfma_f32_16x16x32_bf16 v[126:129], v[156:159], v[190:193], v[126:129]
	v_mfma_f32_16x16x32_bf16 v[126:129], v[160:163], v[194:197], v[126:129]
	v_mfma_f32_16x16x32_bf16 v[122:125], v[168:171], v[194:197], v[122:125]
	v_mfma_f32_16x16x32_bf16 v[122:125], v[164:167], v[190:193], v[122:125]
	v_mfma_f32_16x16x32_bf16 v[118:121], v[174:177], v[190:193], v[118:121]
	v_mfma_f32_16x16x32_bf16 v[118:121], v[178:181], v[194:197], v[118:121]
	v_mfma_f32_16x16x32_bf16 v[114:117], v[186:189], v[194:197], v[114:117]
	v_mfma_f32_16x16x32_bf16 v[114:117], v[182:185], v[190:193], v[114:117]
	v_mfma_f32_16x16x32_bf16 v[98:101], v[182:185], v[198:201], v[98:101]
	v_mfma_f32_16x16x32_bf16 v[98:101], v[186:189], v[202:205], v[98:101]
	v_mfma_f32_16x16x32_bf16 v[102:105], v[178:181], v[202:205], v[102:105]
	v_mfma_f32_16x16x32_bf16 v[102:105], v[174:177], v[198:201], v[102:105]
	v_mfma_f32_16x16x32_bf16 v[106:109], v[164:167], v[198:201], v[106:109]
	v_mfma_f32_16x16x32_bf16 v[106:109], v[168:171], v[202:205], v[106:109]
	v_mfma_f32_16x16x32_bf16 v[110:113], v[160:163], v[202:205], v[110:113]
	v_mfma_f32_16x16x32_bf16 v[110:113], v[156:159], v[198:201], v[110:113]
	v_mfma_f32_16x16x32_bf16 v[94:97], v[156:159], v[206:209], v[94:97]
	v_mfma_f32_16x16x32_bf16 v[94:97], v[160:163], v[210:213], v[94:97]
	v_mfma_f32_16x16x32_bf16 v[90:93], v[168:171], v[210:213], v[90:93]
	v_mfma_f32_16x16x32_bf16 v[90:93], v[164:167], v[206:209], v[90:93]
	v_mfma_f32_16x16x32_bf16 v[86:89], v[174:177], v[206:209], v[86:89]
	v_mfma_f32_16x16x32_bf16 v[86:89], v[178:181], v[210:213], v[86:89]
	v_mfma_f32_16x16x32_bf16 v[82:85], v[186:189], v[210:213], v[82:85]
	v_mfma_f32_16x16x32_bf16 v[82:85], v[182:185], v[206:209], v[82:85]
	v_mfma_f32_16x16x32_bf16 v[66:69], v[182:185], v[214:217], v[66:69]
	v_mfma_f32_16x16x32_bf16 v[66:69], v[186:189], v[218:221], v[66:69]
	v_mfma_f32_16x16x32_bf16 v[70:73], v[178:181], v[218:221], v[70:73]
	v_mfma_f32_16x16x32_bf16 v[70:73], v[174:177], v[214:217], v[70:73]
	v_mfma_f32_16x16x32_bf16 v[74:77], v[164:167], v[214:217], v[74:77]
	v_mfma_f32_16x16x32_bf16 v[74:77], v[168:171], v[218:221], v[74:77]
	v_mfma_f32_16x16x32_bf16 v[78:81], v[160:163], v[218:221], v[78:81]
	v_mfma_f32_16x16x32_bf16 v[78:81], v[156:159], v[214:217], v[78:81]
	v_mfma_f32_16x16x32_bf16 v[62:65], v[156:159], v[222:225], v[62:65]
	v_mfma_f32_16x16x32_bf16 v[62:65], v[160:163], v[226:229], v[62:65]
	v_mfma_f32_16x16x32_bf16 v[58:61], v[168:171], v[226:229], v[58:61]
	v_mfma_f32_16x16x32_bf16 v[58:61], v[164:167], v[222:225], v[58:61]
	v_mfma_f32_16x16x32_bf16 v[54:57], v[174:177], v[222:225], v[54:57]
	v_mfma_f32_16x16x32_bf16 v[54:57], v[178:181], v[226:229], v[54:57]
	v_mfma_f32_16x16x32_bf16 v[50:53], v[186:189], v[226:229], v[50:53]
	v_mfma_f32_16x16x32_bf16 v[50:53], v[182:185], v[222:225], v[50:53]
	v_mfma_f32_16x16x32_bf16 v[34:37], v[182:185], v[230:233], v[34:37]
	v_mfma_f32_16x16x32_bf16 v[34:37], v[186:189], v[234:237], v[34:37]
	v_mfma_f32_16x16x32_bf16 v[38:41], v[178:181], v[234:237], v[38:41]
	v_mfma_f32_16x16x32_bf16 v[38:41], v[174:177], v[230:233], v[38:41]
	v_mfma_f32_16x16x32_bf16 v[42:45], v[164:167], v[230:233], v[42:45]
	v_mfma_f32_16x16x32_bf16 v[42:45], v[168:171], v[234:237], v[42:45]
	v_mfma_f32_16x16x32_bf16 v[46:49], v[160:163], v[234:237], v[46:49]
	v_mfma_f32_16x16x32_bf16 v[46:49], v[156:159], v[230:233], v[46:49]
	v_mfma_f32_16x16x32_bf16 v[30:33], v[156:159], v[238:241], v[30:33]
	v_mfma_f32_16x16x32_bf16 v[30:33], v[160:163], v[242:245], v[30:33]
	v_mfma_f32_16x16x32_bf16 v[26:29], v[168:171], v[242:245], v[26:29]
	v_mfma_f32_16x16x32_bf16 v[26:29], v[164:167], v[238:241], v[26:29]
	v_mfma_f32_16x16x32_bf16 v[22:25], v[174:177], v[238:241], v[22:25]
	v_mfma_f32_16x16x32_bf16 v[22:25], v[178:181], v[242:245], v[22:25]
	v_mfma_f32_16x16x32_bf16 v[18:21], v[186:189], v[242:245], v[18:21]
	v_mfma_f32_16x16x32_bf16 v[18:21], v[182:185], v[238:241], v[18:21]
	v_mfma_f32_16x16x32_bf16 v[2:5], v[182:185], v[246:249], v[2:5]
	v_mfma_f32_16x16x32_bf16 v[2:5], v[186:189], v[250:253], v[2:5]
	v_mfma_f32_16x16x32_bf16 v[6:9], v[178:181], v[250:253], v[6:9]
	v_mfma_f32_16x16x32_bf16 v[6:9], v[174:177], v[246:249], v[6:9]
	v_mfma_f32_16x16x32_bf16 v[10:13], v[164:167], v[246:249], v[10:13]
	v_mfma_f32_16x16x32_bf16 v[10:13], v[168:171], v[250:253], v[10:13]
	v_mfma_f32_16x16x32_bf16 v[14:17], v[160:163], v[250:253], v[14:17]
	v_mfma_f32_16x16x32_bf16 v[14:17], v[156:159], v[246:249], v[14:17]
	s_setprio 0
	s_waitcnt vmcnt(0)
	s_barrier
; #define PG8_STAGE(bufoff, gbase, voff) do { _Pragma("unroll") for (int _i = 0; _i < 2; ++_i) \
;         __builtin_amdgcn_global_load_lds((const unsigned*)((const char*)(gbase) + (voff)[_i]), (PG8_LAS unsigned*)(lds + (bufoff) + ldsw + _i * 8192), 16, 0, 0); } while (0)
; #define PG8_LDA(dst, b, h) do { _Pragma("unroll") for (int m = 0; m < 4; ++m) _Pragma("unroll") for (int k = 0; k < 2; ++k) dst[m][k] = *(const PG8_LAS bf16x8*)(lds + PG8_SA(b, h) + aoff + m * 2048 + k * 1024); } while (0)
; #define PG8_LDB(dst, b, h) do { _Pragma("unroll") for (int n = 0; n < 2; ++n) _Pragma("unroll") for (int k = 0; k < 2; ++k) dst[n][k] = *(const PG8_LAS bf16x8*)(lds + PG8_SB(b, h) + boff + n * 2048 + k * 1024); } while (0)
; #define PG8_MMA(ai, bj, At, Bt) do { __builtin_amdgcn_s_setprio(1); _Pragma("unroll") for (int m = 0; m < 4; ++m) _Pragma("unroll") for (int n = 0; n < 2; ++n) _Pragma("unroll") for (int k = 0; k < 2; ++k) \
;         acc[ai][bj][m][n] = __builtin_amdgcn_mfma_f32_16x16x32_bf16(Bt[n][k], At[m][k], acc[ai][bj][m][n], 0, 0, 0); __builtin_amdgcn_s_setprio(0); } while (0)
; #define PG8_WAIT_V(n) asm volatile("s_waitcnt vmcnt(" #n ")" ::: "memory")
; #define PG8_WAIT_L(n) asm volatile("s_waitcnt lgkmcnt(" #n ")" ::: "memory")
; #define PG8_BAR __builtin_amdgcn_s_barrier()
; #define PG8_SCHED __builtin_amdgcn_sched_barrier(0)
; template <class Epi, class Sched, bool ALIGN_EPI>
; __device__ __forceinline__ void gemm_phase(PG8_LAS unsigned char* lds, const Gemm g, const Sched& S, const Epi& E) {
;     ...
;             PG8_LDB(B0, 1, 0); PG8_LDB(B1, 1, 1); PG8_SCHED; PG8_LDA(At, 1, 0); PG8_STAGE(PG8_SA(0, 1), a2 + hstepA, voffA);
;             PG8_WAIT_V(8); PG8_WAIT_L(0); PG8_BAR; PG8_MMA(0, 0, At, B0); PG8_MMA(0, 1, At, B1); PG8_BAR; PG8_SCHED;
;             PG8_LDA(At, 1, 1); PG8_STAGE(PG8_SB(1, 0), b3, voffB); PG8_STAGE(PG8_SB(1, 1), b3 + hstepB, voffB); PG8_STAGE(PG8_SA(1, 0), a3, voffA);
;             PG8_WAIT_V(8); PG8_WAIT_L(0); PG8_BAR; PG8_MMA(1, 0, At, B0); PG8_MMA(1, 1, At, B1); PG8_BAR; PG8_SCHED;
;         }
	s_cmp_eq_u32 s49, 15
	s_cselect_b32 s28, s50, s28
	s_cselect_b32 s29, s51, s29
	s_add_i32 m0, s2, 0x2000
	s_nop 0
	global_load_lds_dwordx4 v132, s[28:29]
	s_add_u32 s30, s28, 0x20000
	s_addc_u32 s31, s29, 0
	s_add_i32 m0, s2, 0x3000
	s_nop 0
	global_load_lds_dwordx4 v132, s[30:31]
	s_add_u32 s30, s28, 0x80000
	s_addc_u32 s31, s29, 0
	s_add_i32 m0, s2, 0x6000
	s_nop 0
	global_load_lds_dwordx4 v132, s[30:31]
	s_add_u32 s30, s28, 0xa0000
	s_addc_u32 s31, s29, 0
	s_add_i32 m0, s2, 0x7000
	s_nop 0
	global_load_lds_dwordx4 v132, s[30:31]
	s_add_u32 s34, s28, 0x80
	s_addc_u32 s35, s29, 0
	s_add_i32 m0, s2, 0x8000
	s_nop 0
	global_load_lds_dwordx4 v136, s[34:35]
	s_add_u32 s30, s34, 0x20000
	s_addc_u32 s31, s35, 0
	s_add_i32 m0, s2, 0x9000
	s_nop 0
	global_load_lds_dwordx4 v136, s[30:31]
	s_add_u32 s30, s34, 0x80000
	s_addc_u32 s31, s35, 0
	s_add_i32 m0, s2, 0xc000
	s_nop 0
	global_load_lds_dwordx4 v136, s[30:31]
	s_add_u32 s30, s34, 0xa0000
	s_addc_u32 s31, s35, 0
	s_add_i32 m0, s2, 0xd000
	s_nop 0
	global_load_lds_dwordx4 v136, s[30:31]
	s_add_u32 s28, s28, 0x80
	s_addc_u32 s29, s29, 0
	ds_read_b128 v[190:193], v155 offset:32768
	ds_read_b128 v[194:197], v155 offset:33792
	ds_read_b128 v[198:201], v155 offset:34816
	ds_read_b128 v[202:205], v155 offset:35840
	ds_read_b128 v[206:209], v155 offset:36864
	ds_read_b128 v[210:213], v155 offset:37888
	ds_read_b128 v[214:217], v155 offset:38912
	ds_read_b128 v[218:221], v155 offset:39936
	ds_read_b128 v[156:159], v153 offset:32768
	ds_read_b128 v[160:163], v153 offset:33792
	ds_read_b128 v[164:167], v153 offset:34816
	ds_read_b128 v[168:171], v153 offset:35840
	ds_read_b128 v[174:177], v153 offset:49152
	ds_read_b128 v[178:181], v153 offset:50176
	ds_read_b128 v[182:185], v153 offset:51200
	ds_read_b128 v[186:189], v153 offset:52224
	ds_read_b128 v[222:225], v155 offset:49152
	ds_read_b128 v[226:229], v155 offset:50176
	ds_read_b128 v[230:233], v155 offset:51200
	ds_read_b128 v[234:237], v155 offset:52224
	ds_read_b128 v[238:241], v155 offset:53248
	ds_read_b128 v[242:245], v155 offset:54272
	ds_read_b128 v[246:249], v155 offset:55296
	ds_read_b128 v[250:253], v155 offset:56320
	s_waitcnt vmcnt(8) lgkmcnt(0)
	s_barrier
	s_setprio 1
	v_mfma_f32_16x16x32_bf16 v[126:129], v[156:159], v[190:193], v[126:129]
	v_mfma_f32_16x16x32_bf16 v[126:129], v[160:163], v[194:197], v[126:129]
	v_mfma_f32_16x16x32_bf16 v[122:125], v[168:171], v[194:197], v[122:125]
	v_mfma_f32_16x16x32_bf16 v[122:125], v[164:167], v[190:193], v[122:125]
	v_mfma_f32_16x16x32_bf16 v[118:121], v[174:177], v[190:193], v[118:121]
	v_mfma_f32_16x16x32_bf16 v[118:121], v[178:181], v[194:197], v[118:121]
	v_mfma_f32_16x16x32_bf16 v[114:117], v[186:189], v[194:197], v[114:117]
	v_mfma_f32_16x16x32_bf16 v[114:117], v[182:185], v[190:193], v[114:117]
	v_mfma_f32_16x16x32_bf16 v[98:101], v[182:185], v[198:201], v[98:101]
	v_mfma_f32_16x16x32_bf16 v[98:101], v[186:189], v[202:205], v[98:101]
	v_mfma_f32_16x16x32_bf16 v[102:105], v[178:181], v[202:205], v[102:105]
	v_mfma_f32_16x16x32_bf16 v[102:105], v[174:177], v[198:201], v[102:105]
	v_mfma_f32_16x16x32_bf16 v[106:109], v[164:167], v[198:201], v[106:109]
	v_mfma_f32_16x16x32_bf16 v[106:109], v[168:171], v[202:205], v[106:109]
	v_mfma_f32_16x16x32_bf16 v[110:113], v[160:163], v[202:205], v[110:113]
	v_mfma_f32_16x16x32_bf16 v[110:113], v[156:159], v[198:201], v[110:113]
	v_mfma_f32_16x16x32_bf16 v[94:97], v[156:159], v[206:209], v[94:97]
	v_mfma_f32_16x16x32_bf16 v[94:97], v[160:163], v[210:213], v[94:97]
	v_mfma_f32_16x16x32_bf16 v[90:93], v[168:171], v[210:213], v[90:93]
	v_mfma_f32_16x16x32_bf16 v[90:93], v[164:167], v[206:209], v[90:93]
	v_mfma_f32_16x16x32_bf16 v[86:89], v[174:177], v[206:209], v[86:89]
	v_mfma_f32_16x16x32_bf16 v[86:89], v[178:181], v[210:213], v[86:89]
	v_mfma_f32_16x16x32_bf16 v[82:85], v[186:189], v[210:213], v[82:85]
	v_mfma_f32_16x16x32_bf16 v[82:85], v[182:185], v[206:209], v[82:85]
	v_mfma_f32_16x16x32_bf16 v[66:69], v[182:185], v[214:217], v[66:69]
	v_mfma_f32_16x16x32_bf16 v[66:69], v[186:189], v[218:221], v[66:69]
	v_mfma_f32_16x16x32_bf16 v[70:73], v[178:181], v[218:221], v[70:73]
	v_mfma_f32_16x16x32_bf16 v[70:73], v[174:177], v[214:217], v[70:73]
	v_mfma_f32_16x16x32_bf16 v[74:77], v[164:167], v[214:217], v[74:77]
	v_mfma_f32_16x16x32_bf16 v[74:77], v[168:171], v[218:221], v[74:77]
	v_mfma_f32_16x16x32_bf16 v[78:81], v[160:163], v[218:221], v[78:81]
	v_mfma_f32_16x16x32_bf16 v[78:81], v[156:159], v[214:217], v[78:81]
	v_mfma_f32_16x16x32_bf16 v[62:65], v[156:159], v[222:225], v[62:65]
	v_mfma_f32_16x16x32_bf16 v[62:65], v[160:163], v[226:229], v[62:65]
	v_mfma_f32_16x16x32_bf16 v[58:61], v[168:171], v[226:229], v[58:61]
	v_mfma_f32_16x16x32_bf16 v[58:61], v[164:167], v[222:225], v[58:61]
	v_mfma_f32_16x16x32_bf16 v[54:57], v[174:177], v[222:225], v[54:57]
	v_mfma_f32_16x16x32_bf16 v[54:57], v[178:181], v[226:229], v[54:57]
	v_mfma_f32_16x16x32_bf16 v[50:53], v[186:189], v[226:229], v[50:53]
	v_mfma_f32_16x16x32_bf16 v[50:53], v[182:185], v[222:225], v[50:53]
	v_mfma_f32_16x16x32_bf16 v[34:37], v[182:185], v[230:233], v[34:37]
	v_mfma_f32_16x16x32_bf16 v[34:37], v[186:189], v[234:237], v[34:37]
	v_mfma_f32_16x16x32_bf16 v[38:41], v[178:181], v[234:237], v[38:41]
	v_mfma_f32_16x16x32_bf16 v[38:41], v[174:177], v[230:233], v[38:41]
	v_mfma_f32_16x16x32_bf16 v[42:45], v[164:167], v[230:233], v[42:45]
	v_mfma_f32_16x16x32_bf16 v[42:45], v[168:171], v[234:237], v[42:45]
	v_mfma_f32_16x16x32_bf16 v[46:49], v[160:163], v[234:237], v[46:49]
	v_mfma_f32_16x16x32_bf16 v[46:49], v[156:159], v[230:233], v[46:49]
	v_mfma_f32_16x16x32_bf16 v[30:33], v[156:159], v[238:241], v[30:33]
	v_mfma_f32_16x16x32_bf16 v[30:33], v[160:163], v[242:245], v[30:33]
	v_mfma_f32_16x16x32_bf16 v[26:29], v[168:171], v[242:245], v[26:29]
	v_mfma_f32_16x16x32_bf16 v[26:29], v[164:167], v[238:241], v[26:29]
	v_mfma_f32_16x16x32_bf16 v[22:25], v[174:177], v[238:241], v[22:25]
	v_mfma_f32_16x16x32_bf16 v[22:25], v[178:181], v[242:245], v[22:25]
	v_mfma_f32_16x16x32_bf16 v[18:21], v[186:189], v[242:245], v[18:21]
	v_mfma_f32_16x16x32_bf16 v[18:21], v[182:185], v[238:241], v[18:21]
	v_mfma_f32_16x16x32_bf16 v[2:5], v[182:185], v[246:249], v[2:5]
	v_mfma_f32_16x16x32_bf16 v[2:5], v[186:189], v[250:253], v[2:5]
	v_mfma_f32_16x16x32_bf16 v[6:9], v[178:181], v[250:253], v[6:9]
	v_mfma_f32_16x16x32_bf16 v[6:9], v[174:177], v[246:249], v[6:9]
	v_mfma_f32_16x16x32_bf16 v[10:13], v[164:167], v[246:249], v[10:13]
	v_mfma_f32_16x16x32_bf16 v[10:13], v[168:171], v[250:253], v[10:13]
	v_mfma_f32_16x16x32_bf16 v[14:17], v[160:163], v[250:253], v[14:17]
	v_mfma_f32_16x16x32_bf16 v[14:17], v[156:159], v[246:249], v[14:17]
	s_setprio 0
	s_waitcnt vmcnt(0)
	s_barrier
	s_add_i32 s49, s49, 1
	s_cmp_lt_u32 s49, 16
	s_cbranch_scc1 .Lp8k_B_loop
